# v23: v20 + 64-byte alignment of the 8 GEMM K-loop head labels (code placement)
# speedup vs baseline: 1.0055x; 1.0034x over previous
; template <class Epi, class Sched, bool ALIGN_EPI = false, bool SP2 = false>
; __device__ __forceinline__ void gemm_phase(PG8_LAS unsigned char* lds, const Gemm g, const Sched& S, const Epi& E) {
;     ...
;         const char* nA = has_next ? (const char*)g.A + (size_t)nxt.pm * tstep + nxt.ko : cA; const char* nB = has_next ? (const char*)g.Bt + (size_t)nxt.pn * tstep + nxt.ko : cB;
;         for (int t = 0; t < nt; t += 2) {
;             const bool last = (t == nt - 2);
;             const char* a1 = cA + (size_t)(t + 1) * kstep;
;             const char* a2 = last ? nA : cA + (size_t)(t + 2) * kstep; const char* b2 = last ? nB : cB + (size_t)(t + 2) * kstep;
;             const char* a3 = a2 + kstep; const char* b3 = b2 + kstep;
;     ...
; #pragma unroll
;         for (int a = 0; a < 2; ++a)
; #pragma unroll
;             for (int b = 0; b < 2; ++b)
; #pragma unroll
;                 for (int m = 0; m < 4; ++m)
; #pragma unroll
;                     for (int n = 0; n < 2; ++n) acc[a][b][m][n] = (f32x4){0.f, 0.f, 0.f, 0.f};
;         cur = nxt; cA = nA; cB = nB; ++ui;
.LBB0_166:
	v_mov_b32_e32 v123, 0
	s_andn2_b64 vcc, exec, s[40:41]
	v_mov_b32_e32 v122, v123
	v_mov_b32_e32 v121, v123
	v_mov_b32_e32 v120, v123
	v_mov_b32_e32 v127, v123
	v_mov_b32_e32 v126, v123
	v_mov_b32_e32 v125, v123
	v_mov_b32_e32 v124, v123
	v_mov_b32_e32 v115, v123
	v_mov_b32_e32 v114, v123
	v_mov_b32_e32 v113, v123
	v_mov_b32_e32 v112, v123
	v_mov_b32_e32 v119, v123
	v_mov_b32_e32 v118, v123
	v_mov_b32_e32 v117, v123
	v_mov_b32_e32 v116, v123
	v_mov_b32_e32 v107, v123
	v_mov_b32_e32 v106, v123
	v_mov_b32_e32 v105, v123
	v_mov_b32_e32 v104, v123
	v_mov_b32_e32 v111, v123
	v_mov_b32_e32 v110, v123
	v_mov_b32_e32 v109, v123
	v_mov_b32_e32 v108, v123
	v_mov_b32_e32 v99, v123
	v_mov_b32_e32 v98, v123
	v_mov_b32_e32 v97, v123
	v_mov_b32_e32 v96, v123
	v_mov_b32_e32 v103, v123
	v_mov_b32_e32 v102, v123
	s_waitcnt lgkmcnt(0)
	v_mov_b64_e32 v[0:1], 0
	v_mov_b64_e32 v[2:3], 0
	v_mov_b64_e32 v[4:5], 0
	v_mov_b64_e32 v[6:7], 0
	v_mov_b64_e32 v[8:9], 0
	v_mov_b64_e32 v[10:11], 0
	v_mov_b64_e32 v[12:13], 0
	v_mov_b64_e32 v[14:15], 0
	v_mov_b64_e32 v[16:17], 0
	v_mov_b64_e32 v[18:19], 0
	v_mov_b64_e32 v[20:21], 0
	v_mov_b64_e32 v[22:23], 0
	v_mov_b64_e32 v[24:25], 0
	v_mov_b64_e32 v[26:27], 0
	v_mov_b64_e32 v[28:29], 0
	v_mov_b64_e32 v[30:31], 0
	v_mov_b64_e32 v[32:33], 0
	v_mov_b64_e32 v[34:35], 0
	v_mov_b64_e32 v[36:37], 0
	v_mov_b64_e32 v[38:39], 0
	v_mov_b64_e32 v[40:41], 0
	v_mov_b64_e32 v[42:43], 0
	v_mov_b64_e32 v[44:45], 0
	v_mov_b64_e32 v[46:47], 0
	v_mov_b64_e32 v[48:49], 0
	v_mov_b64_e32 v[50:51], 0
	v_mov_b64_e32 v[52:53], 0
	v_mov_b64_e32 v[54:55], 0
	v_mov_b64_e32 v[56:57], 0
	v_mov_b64_e32 v[58:59], 0
	v_mov_b64_e32 v[60:61], 0
	v_mov_b64_e32 v[62:63], 0
	v_mov_b64_e32 v[64:65], 0
	v_mov_b64_e32 v[66:67], 0
	v_mov_b64_e32 v[68:69], 0
	v_mov_b64_e32 v[70:71], 0
	v_mov_b64_e32 v[72:73], 0
	v_mov_b64_e32 v[74:75], 0
	v_mov_b64_e32 v[76:77], 0
	v_mov_b64_e32 v[78:79], 0
	v_mov_b64_e32 v[80:81], 0
	v_mov_b64_e32 v[82:83], 0
	v_mov_b64_e32 v[84:85], 0
	v_mov_b64_e32 v[86:87], 0
	v_mov_b64_e32 v[88:89], 0
	v_mov_b64_e32 v[90:91], 0
	v_mov_b64_e32 v[92:93], 0
	v_mov_b64_e32 v[94:95], 0
	v_mov_b64_e32 v[100:101], 0
	v_mov_b32_e32 v123, 0
	s_cbranch_vccnz .LBB0_169
	s_add_u32 s0, s0, 0x80
	s_addc_u32 s1, s1, 0
	s_add_u32 s8, s8, 0x100
	v_mov_b32_e32 v0, 0
	s_addc_u32 s9, s9, 0
	s_mov_b32 s6, 0
	v_mov_b64_e32 v[0:1], 0
	v_mov_b64_e32 v[2:3], 0
	v_mov_b64_e32 v[4:5], 0
	v_mov_b64_e32 v[6:7], 0
	v_mov_b64_e32 v[8:9], 0
	v_mov_b64_e32 v[10:11], 0
	v_mov_b64_e32 v[12:13], 0
	v_mov_b64_e32 v[14:15], 0
	v_mov_b64_e32 v[16:17], 0
	v_mov_b64_e32 v[18:19], 0
	v_mov_b64_e32 v[20:21], 0
	v_mov_b64_e32 v[22:23], 0
	v_mov_b64_e32 v[24:25], 0
	v_mov_b64_e32 v[26:27], 0
	v_mov_b64_e32 v[28:29], 0
	v_mov_b64_e32 v[30:31], 0
	v_mov_b64_e32 v[32:33], 0
	v_mov_b64_e32 v[34:35], 0
	v_mov_b64_e32 v[36:37], 0
	v_mov_b64_e32 v[38:39], 0
	v_mov_b64_e32 v[40:41], 0
	v_mov_b64_e32 v[42:43], 0
	v_mov_b64_e32 v[44:45], 0
	v_mov_b64_e32 v[46:47], 0
	v_mov_b64_e32 v[48:49], 0
	v_mov_b64_e32 v[50:51], 0
	v_mov_b64_e32 v[52:53], 0
	v_mov_b64_e32 v[54:55], 0
	v_mov_b64_e32 v[56:57], 0
	v_mov_b64_e32 v[58:59], 0
	v_mov_b64_e32 v[60:61], 0
	v_mov_b64_e32 v[62:63], 0
	v_mov_b64_e32 v[64:65], 0
	v_mov_b64_e32 v[66:67], 0
	v_mov_b64_e32 v[68:69], 0
	v_mov_b64_e32 v[70:71], 0
	v_mov_b64_e32 v[72:73], 0
	v_mov_b64_e32 v[74:75], 0
	v_mov_b64_e32 v[76:77], 0
	v_mov_b64_e32 v[78:79], 0
	v_mov_b64_e32 v[80:81], 0
	v_mov_b64_e32 v[82:83], 0
	v_mov_b64_e32 v[84:85], 0
	v_mov_b64_e32 v[86:87], 0
	v_mov_b64_e32 v[88:89], 0
	v_mov_b64_e32 v[90:91], 0
	v_mov_b64_e32 v[92:93], 0
	v_mov_b64_e32 v[94:95], 0
	v_mov_b64_e32 v[96:97], 0
	v_mov_b64_e32 v[98:99], 0
	v_mov_b64_e32 v[100:101], 0
	v_mov_b64_e32 v[102:103], 0
	v_mov_b64_e32 v[104:105], 0
	v_mov_b64_e32 v[106:107], 0
	v_mov_b64_e32 v[108:109], 0
	v_mov_b64_e32 v[110:111], 0
	v_mov_b64_e32 v[112:113], 0
	v_mov_b64_e32 v[114:115], 0
	v_mov_b64_e32 v[116:117], 0
	v_mov_b64_e32 v[118:119], 0
	v_mov_b64_e32 v[120:121], 0
	v_mov_b64_e32 v[122:123], 0
	v_mov_b64_e32 v[124:125], 0
	v_mov_b64_e32 v[126:127], 0
	.p2align	6

; template <class Epi, class Sched, bool ALIGN_EPI = false, bool SP2 = false>
; __device__ __forceinline__ void gemm_phase(PG8_LAS unsigned char* lds, const Gemm g, const Sched& S, const Epi& E) {
;     ...
;         const char* nA = has_next ? (const char*)g.A + (size_t)nxt.pm * tstep + nxt.ko : cA; const char* nB = has_next ? (const char*)g.Bt + (size_t)nxt.pn * tstep + nxt.ko : cB;
;         for (int t = 0; t < nt; t += 2) {
;             const bool last = (t == nt - 2);
;             const char* a1 = cA + (size_t)(t + 1) * kstep;
;             const char* a2 = last ? nA : cA + (size_t)(t + 2) * kstep; const char* b2 = last ? nB : cB + (size_t)(t + 2) * kstep;
;             const char* a3 = a2 + kstep; const char* b3 = b2 + kstep;
;     ...
; #pragma unroll
;         for (int a = 0; a < 2; ++a)
; #pragma unroll
;             for (int b = 0; b < 2; ++b)
; #pragma unroll
;                 for (int m = 0; m < 4; ++m)
; #pragma unroll
;                     for (int n = 0; n < 2; ++n) acc[a][b][m][n] = (f32x4){0.f, 0.f, 0.f, 0.f};
;         cur = nxt; cA = nA; cB = nB; ++ui;
.LBB0_373:
	v_mov_b32_e32 v123, 0
	s_andn2_b64 vcc, exec, s[26:27]
	v_mov_b64_e32 v[0:1], 0
	v_mov_b64_e32 v[2:3], 0
	v_mov_b64_e32 v[4:5], 0
	v_mov_b64_e32 v[6:7], 0
	v_mov_b64_e32 v[8:9], 0
	v_mov_b64_e32 v[10:11], 0
	v_mov_b64_e32 v[12:13], 0
	v_mov_b64_e32 v[14:15], 0
	v_mov_b64_e32 v[16:17], 0
	v_mov_b64_e32 v[18:19], 0
	v_mov_b64_e32 v[20:21], 0
	v_mov_b64_e32 v[22:23], 0
	v_mov_b64_e32 v[24:25], 0
	v_mov_b64_e32 v[26:27], 0
	v_mov_b64_e32 v[28:29], 0
	v_mov_b64_e32 v[30:31], 0
	v_mov_b64_e32 v[32:33], 0
	v_mov_b64_e32 v[34:35], 0
	v_mov_b64_e32 v[36:37], 0
	v_mov_b64_e32 v[38:39], 0
	v_mov_b64_e32 v[40:41], 0
	v_mov_b64_e32 v[42:43], 0
	v_mov_b64_e32 v[44:45], 0
	v_mov_b64_e32 v[46:47], 0
	v_mov_b64_e32 v[48:49], 0
	v_mov_b64_e32 v[50:51], 0
	v_mov_b64_e32 v[52:53], 0
	v_mov_b64_e32 v[54:55], 0
	v_mov_b64_e32 v[56:57], 0
	v_mov_b64_e32 v[58:59], 0
	v_mov_b64_e32 v[60:61], 0
	v_mov_b64_e32 v[62:63], 0
	v_mov_b64_e32 v[64:65], 0
	v_mov_b64_e32 v[66:67], 0
	v_mov_b64_e32 v[68:69], 0
	v_mov_b64_e32 v[70:71], 0
	v_mov_b64_e32 v[72:73], 0
	v_mov_b64_e32 v[74:75], 0
	v_mov_b64_e32 v[76:77], 0
	v_mov_b64_e32 v[78:79], 0
	v_mov_b64_e32 v[80:81], 0
	v_mov_b64_e32 v[82:83], 0
	v_mov_b64_e32 v[84:85], 0
	v_mov_b64_e32 v[86:87], 0
	v_mov_b64_e32 v[88:89], 0
	v_mov_b64_e32 v[90:91], 0
	v_mov_b64_e32 v[92:93], 0
	v_mov_b64_e32 v[94:95], 0
	v_mov_b64_e32 v[96:97], 0
	v_mov_b64_e32 v[98:99], 0
	v_mov_b64_e32 v[100:101], 0
	v_mov_b64_e32 v[102:103], 0
	v_mov_b64_e32 v[104:105], 0
	v_mov_b64_e32 v[106:107], 0
	v_mov_b64_e32 v[108:109], 0
	v_mov_b64_e32 v[110:111], 0
	v_mov_b64_e32 v[112:113], 0
	v_mov_b64_e32 v[114:115], 0
	v_mov_b64_e32 v[116:117], 0
	v_mov_b64_e32 v[118:119], 0
	v_mov_b64_e32 v[120:121], 0
	v_mov_b64_e32 v[122:123], 0
	v_mov_b64_e32 v[124:125], 0
	v_mov_b64_e32 v[126:127], 0
	s_cbranch_vccnz .LBB0_377
	s_add_u32 s40, s40, 0x80
	s_addc_u32 s41, s41, 0
	s_add_u32 s78, s64, 0x100
	v_mov_b32_e32 v0, 0
	s_addc_u32 s79, s65, 0
	s_mov_b32 s64, 0
	v_mov_b64_e32 v[0:1], 0
	v_mov_b64_e32 v[2:3], 0
	v_mov_b64_e32 v[4:5], 0
	v_mov_b64_e32 v[6:7], 0
	v_mov_b64_e32 v[8:9], 0
	v_mov_b64_e32 v[10:11], 0
	v_mov_b64_e32 v[12:13], 0
	v_mov_b64_e32 v[14:15], 0
	v_mov_b64_e32 v[16:17], 0
	v_mov_b64_e32 v[18:19], 0
	v_mov_b64_e32 v[20:21], 0
	v_mov_b64_e32 v[22:23], 0
	v_mov_b64_e32 v[24:25], 0
	v_mov_b64_e32 v[26:27], 0
	v_mov_b64_e32 v[28:29], 0
	v_mov_b64_e32 v[30:31], 0
	v_mov_b64_e32 v[32:33], 0
	v_mov_b64_e32 v[34:35], 0
	v_mov_b64_e32 v[36:37], 0
	v_mov_b64_e32 v[38:39], 0
	v_mov_b64_e32 v[40:41], 0
	v_mov_b64_e32 v[42:43], 0
	v_mov_b64_e32 v[44:45], 0
	v_mov_b64_e32 v[46:47], 0
	v_mov_b64_e32 v[48:49], 0
	v_mov_b64_e32 v[50:51], 0
	v_mov_b64_e32 v[52:53], 0
	v_mov_b64_e32 v[54:55], 0
	v_mov_b64_e32 v[56:57], 0
	v_mov_b64_e32 v[58:59], 0
	v_mov_b64_e32 v[60:61], 0
	v_mov_b64_e32 v[62:63], 0
	v_mov_b64_e32 v[64:65], 0
	v_mov_b64_e32 v[66:67], 0
	v_mov_b64_e32 v[68:69], 0
	v_mov_b64_e32 v[70:71], 0
	v_mov_b64_e32 v[72:73], 0
	v_mov_b64_e32 v[74:75], 0
	v_mov_b64_e32 v[76:77], 0
	v_mov_b64_e32 v[78:79], 0
	v_mov_b64_e32 v[80:81], 0
	v_mov_b64_e32 v[82:83], 0
	v_mov_b64_e32 v[84:85], 0
	v_mov_b64_e32 v[86:87], 0
	v_mov_b64_e32 v[88:89], 0
	v_mov_b64_e32 v[90:91], 0
	v_mov_b64_e32 v[92:93], 0
	v_mov_b64_e32 v[94:95], 0
	v_mov_b64_e32 v[96:97], 0
	v_mov_b64_e32 v[98:99], 0
	v_mov_b64_e32 v[100:101], 0
	v_mov_b64_e32 v[102:103], 0
	v_mov_b64_e32 v[104:105], 0
	v_mov_b64_e32 v[106:107], 0
	v_mov_b64_e32 v[108:109], 0
	v_mov_b64_e32 v[110:111], 0
	v_mov_b64_e32 v[112:113], 0
	v_mov_b64_e32 v[114:115], 0
	v_mov_b64_e32 v[116:117], 0
	v_mov_b64_e32 v[118:119], 0
	v_mov_b64_e32 v[120:121], 0
	v_mov_b64_e32 v[122:123], 0
	v_mov_b64_e32 v[124:125], 0
	v_mov_b64_e32 v[126:127], 0
	.p2align	6

; template <class Epi, class Sched, bool ALIGN_EPI = false, bool SP2 = false>
; __device__ __forceinline__ void gemm_phase(PG8_LAS unsigned char* lds, const Gemm g, const Sched& S, const Epi& E) {
;     ...
;         const char* nA = has_next ? (const char*)g.A + (size_t)nxt.pm * tstep + nxt.ko : cA; const char* nB = has_next ? (const char*)g.Bt + (size_t)nxt.pn * tstep + nxt.ko : cB;
;         for (int t = 0; t < nt; t += 2) {
;             const bool last = (t == nt - 2);
;             const char* a1 = cA + (size_t)(t + 1) * kstep;
;             const char* a2 = last ? nA : cA + (size_t)(t + 2) * kstep; const char* b2 = last ? nB : cB + (size_t)(t + 2) * kstep;
;             const char* a3 = a2 + kstep; const char* b3 = b2 + kstep;
;     ...
; #pragma unroll
;         for (int a = 0; a < 2; ++a)
; #pragma unroll
;             for (int b = 0; b < 2; ++b)
; #pragma unroll
;                 for (int m = 0; m < 4; ++m)
; #pragma unroll
;                     for (int n = 0; n < 2; ++n) acc[a][b][m][n] = (f32x4){0.f, 0.f, 0.f, 0.f};
;         cur = nxt; cA = nA; cB = nB; ++ui;
.LBB0_404:
	v_mov_b32_e32 v127, 0
	s_andn2_b64 vcc, exec, s[34:35]
	v_mov_b32_e32 v126, 0
	v_mov_b32_e32 v125, 0
	v_mov_b32_e32 v124, 0
	v_mov_b32_e32 v123, 0
	v_mov_b32_e32 v122, 0
	v_mov_b32_e32 v121, 0
	v_mov_b32_e32 v120, 0
	v_mov_b32_e32 v101, 0
	v_mov_b32_e32 v100, 0
	v_mov_b32_e32 v103, 0
	v_mov_b32_e32 v102, 0
	v_mov_b32_e32 v109, 0
	v_mov_b32_e32 v108, 0
	v_mov_b32_e32 v111, 0
	v_mov_b32_e32 v110, 0
	v_mov_b32_e32 v85, 0
	v_mov_b32_e32 v84, 0
	v_mov_b32_e32 v87, 0
	v_mov_b32_e32 v86, 0
	v_mov_b32_e32 v93, 0
	v_mov_b32_e32 v92, 0
	v_mov_b32_e32 v95, 0
	v_mov_b32_e32 v94, 0
	v_mov_b32_e32 v73, 0
	v_mov_b32_e32 v72, 0
	v_mov_b32_e32 v75, 0
	v_mov_b32_e32 v74, 0
	v_mov_b32_e32 v77, 0
	v_mov_b32_e32 v76, 0
	v_mov_b32_e32 v79, 0
	v_mov_b32_e32 v78, 0
	v_mov_b32_e32 v139, 0
	v_mov_b32_e32 v138, 0
	v_mov_b32_e32 v141, 0
	v_mov_b32_e32 v140, 0
	v_mov_b32_e32 v143, 0
	v_mov_b32_e32 v142, 0
	v_mov_b32_e32 v145, 0
	v_mov_b32_e32 v144, 0
	v_mov_b32_e32 v113, 0
	v_mov_b32_e32 v112, 0
	v_mov_b32_e32 v115, 0
	v_mov_b32_e32 v114, 0
	v_mov_b32_e32 v117, 0
	v_mov_b32_e32 v116, 0
	v_mov_b32_e32 v119, 0
	v_mov_b32_e32 v118, 0
	v_mov_b32_e32 v97, 0
	v_mov_b32_e32 v96, 0
	v_mov_b32_e32 v99, 0
	v_mov_b32_e32 v98, 0
	v_mov_b32_e32 v105, 0
	v_mov_b32_e32 v104, 0
	v_mov_b32_e32 v107, 0
	v_mov_b32_e32 v106, 0
	v_mov_b32_e32 v71, 0
	v_mov_b32_e32 v70, 0
	v_mov_b32_e32 v69, 0
	v_mov_b32_e32 v68, 0
	v_mov_b32_e32 v67, 0
	v_mov_b32_e32 v66, 0
	v_mov_b32_e32 v65, 0
	v_mov_b32_e32 v64, 0
	v_mov_b32_e32 v63, 0
	v_mov_b32_e32 v62, 0
	v_mov_b32_e32 v61, 0
	v_mov_b32_e32 v60, 0
	v_mov_b32_e32 v59, 0
	v_mov_b32_e32 v58, 0
	v_mov_b32_e32 v57, 0
	v_mov_b32_e32 v56, 0
	v_mov_b32_e32 v37, 0
	v_mov_b32_e32 v36, 0
	v_mov_b32_e32 v39, 0
	v_mov_b32_e32 v38, 0
	v_mov_b32_e32 v45, 0
	v_mov_b32_e32 v44, 0
	v_mov_b32_e32 v47, 0
	v_mov_b32_e32 v46, 0
	v_mov_b32_e32 v21, 0
	v_mov_b32_e32 v20, 0
	v_mov_b32_e32 v23, 0
	v_mov_b32_e32 v22, 0
	v_mov_b32_e32 v29, 0
	v_mov_b32_e32 v28, 0
	v_mov_b32_e32 v31, 0
	v_mov_b32_e32 v30, 0
	v_mov_b32_e32 v9, 0
	v_mov_b32_e32 v8, 0
	v_mov_b32_e32 v11, 0
	v_mov_b32_e32 v10, 0
	v_mov_b32_e32 v13, 0
	v_mov_b32_e32 v12, 0
	v_mov_b32_e32 v15, 0
	v_mov_b32_e32 v14, 0
	v_mov_b32_e32 v81, 0
	v_mov_b32_e32 v80, 0
	v_mov_b32_e32 v83, 0
	v_mov_b32_e32 v82, 0
	v_mov_b32_e32 v89, 0
	v_mov_b32_e32 v88, 0
	v_mov_b32_e32 v91, 0
	v_mov_b32_e32 v90, 0
	v_mov_b32_e32 v49, 0
	v_mov_b32_e32 v48, 0
	v_mov_b32_e32 v51, 0
	v_mov_b32_e32 v50, 0
	v_mov_b32_e32 v53, 0
	v_mov_b32_e32 v52, 0
	v_mov_b32_e32 v55, 0
	v_mov_b32_e32 v54, 0
	v_mov_b32_e32 v33, 0
	v_mov_b32_e32 v32, 0
	v_mov_b32_e32 v35, 0
	v_mov_b32_e32 v34, 0
	v_mov_b32_e32 v41, 0
	v_mov_b32_e32 v40, 0
	v_mov_b32_e32 v43, 0
	v_mov_b32_e32 v42, 0
	v_mov_b32_e32 v7, 0
	v_mov_b32_e32 v6, 0
	v_mov_b32_e32 v5, 0
	v_mov_b32_e32 v4, 0
	v_mov_b32_e32 v3, 0
	v_mov_b32_e32 v2, 0
	v_mov_b32_e32 v1, 0
	v_mov_b32_e32 v0, 0
	s_cbranch_vccnz .LBB0_408
	s_add_u32 s64, s64, 0x80
	s_addc_u32 s65, s65, 0
	s_add_u32 s79, s66, 0x100
	v_mov_b32_e32 v0, 0
	s_addc_u32 s80, s67, 0
	s_mov_b32 s66, 0
	v_mov_b64_e32 v[0:1], 0
	v_mov_b64_e32 v[2:3], 0
	v_mov_b64_e32 v[4:5], 0
	v_mov_b64_e32 v[6:7], 0
	v_mov_b64_e32 v[8:9], 0
	v_mov_b64_e32 v[10:11], 0
	v_mov_b64_e32 v[12:13], 0
	v_mov_b64_e32 v[14:15], 0
	v_mov_b64_e32 v[16:17], 0
	v_mov_b64_e32 v[18:19], 0
	v_mov_b64_e32 v[20:21], 0
	v_mov_b64_e32 v[22:23], 0
	v_mov_b64_e32 v[24:25], 0
	v_mov_b64_e32 v[26:27], 0
	v_mov_b64_e32 v[28:29], 0
	v_mov_b64_e32 v[30:31], 0
	v_mov_b64_e32 v[32:33], 0
	v_mov_b64_e32 v[34:35], 0
	v_mov_b64_e32 v[36:37], 0
	v_mov_b64_e32 v[38:39], 0
	v_mov_b64_e32 v[40:41], 0
	v_mov_b64_e32 v[42:43], 0
	v_mov_b64_e32 v[44:45], 0
	v_mov_b64_e32 v[46:47], 0
	v_mov_b64_e32 v[48:49], 0
	v_mov_b64_e32 v[50:51], 0
	v_mov_b64_e32 v[52:53], 0
	v_mov_b64_e32 v[54:55], 0
	v_mov_b64_e32 v[56:57], 0
	v_mov_b64_e32 v[58:59], 0
	v_mov_b64_e32 v[60:61], 0
	v_mov_b64_e32 v[62:63], 0
	v_mov_b64_e32 v[64:65], 0
	v_mov_b64_e32 v[66:67], 0
	v_mov_b64_e32 v[68:69], 0
	v_mov_b64_e32 v[70:71], 0
	v_mov_b64_e32 v[72:73], 0
	v_mov_b64_e32 v[74:75], 0
	v_mov_b64_e32 v[76:77], 0
	v_mov_b64_e32 v[78:79], 0
	v_mov_b64_e32 v[80:81], 0
	v_mov_b64_e32 v[82:83], 0
	v_mov_b64_e32 v[84:85], 0
	v_mov_b64_e32 v[86:87], 0
	v_mov_b64_e32 v[88:89], 0
	v_mov_b64_e32 v[90:91], 0
	v_mov_b64_e32 v[92:93], 0
	v_mov_b64_e32 v[94:95], 0
	v_mov_b64_e32 v[96:97], 0
	v_mov_b64_e32 v[98:99], 0
	v_mov_b64_e32 v[100:101], 0
	v_mov_b64_e32 v[102:103], 0
	v_mov_b64_e32 v[104:105], 0
	v_mov_b64_e32 v[106:107], 0
	v_mov_b64_e32 v[108:109], 0
	v_mov_b64_e32 v[110:111], 0
	v_mov_b64_e32 v[112:113], 0
	v_mov_b64_e32 v[114:115], 0
	v_mov_b64_e32 v[116:117], 0
	v_mov_b64_e32 v[118:119], 0
	v_mov_b64_e32 v[120:121], 0
	v_mov_b64_e32 v[122:123], 0
	v_mov_b64_e32 v[124:125], 0
	v_mov_b64_e32 v[126:127], 0
	.p2align	6

; template <class Epi, class Sched, bool ALIGN_EPI = false, bool SP2 = false>
; __device__ __forceinline__ void gemm_phase(PG8_LAS unsigned char* lds, const Gemm g, const Sched& S, const Epi& E) {
;     ...
;         const bool has_next = S.next(ui + 1, nxt);
;         const char* nA = has_next ? (const char*)g.A + (size_t)nxt.pm * tstep + nxt.ko : cA; const char* nB = has_next ? (const char*)g.Bt + (size_t)nxt.pn * tstep + nxt.ko : cB;
;         for (int t = 0; t < nt; t += 2) {
;             const bool last = (t == nt - 2);
;             const char* a1 = cA + (size_t)(t + 1) * kstep;
;             const char* a2 = last ? nA : cA + (size_t)(t + 2) * kstep; const char* b2 = last ? nB : cB + (size_t)(t + 2) * kstep;
;             const char* a3 = a2 + kstep; const char* b3 = b2 + kstep;
;     ...
; #pragma unroll
;         for (int a = 0; a < 2; ++a)
; #pragma unroll
;             for (int b = 0; b < 2; ++b)
; #pragma unroll
;                 for (int m = 0; m < 4; ++m)
; #pragma unroll
;                     for (int n = 0; n < 2; ++n) acc[a][b][m][n] = (f32x4){0.f, 0.f, 0.f, 0.f};
;         cur = nxt; cA = nA; cB = nB; ++ui;
.LBB0_569:
	s_ashr_i32 s27, s26, 31
	s_lshl_b64 s[18:19], s[26:27], 19
	v_readlane_b32 s34, v253, 53
	v_readlane_b32 s35, v253, 54
	s_add_u32 s34, s34, s18
	s_addc_u32 s35, s35, s19
	s_and_b64 s[18:19], s[6:7], exec
	s_cselect_b32 s18, s35, s5
	s_cselect_b32 s19, s34, s4
	s_ashr_i32 s13, s12, 31
	s_lshl_b64 s[36:37], s[12:13], 19
	s_add_u32 s36, s22, s36
	s_addc_u32 s37, s23, s37
	s_and_b64 s[38:39], s[6:7], exec
	s_cselect_b32 s13, s37, s65
	s_cselect_b32 s27, s36, s64
	s_add_u32 s40, s4, 0x40080
	s_addc_u32 s41, s5, 0
	s_add_u32 s70, s64, 0x100
	v_mov_b32_e32 v0, 0
	s_addc_u32 s71, s65, 0
	s_mov_b32 s72, -2
	s_cmp_lg_u32 s67, 1
	s_cbranch_scc1 .Lg2_peel
	v_mov_b64_e32 v[0:1], 0
	v_mov_b64_e32 v[2:3], 0
	v_mov_b64_e32 v[4:5], 0
	v_mov_b64_e32 v[6:7], 0
	v_mov_b64_e32 v[8:9], 0
	v_mov_b64_e32 v[10:11], 0
	v_mov_b64_e32 v[12:13], 0
	v_mov_b64_e32 v[14:15], 0
	v_mov_b64_e32 v[16:17], 0
	v_mov_b64_e32 v[18:19], 0
	v_mov_b64_e32 v[20:21], 0
	v_mov_b64_e32 v[22:23], 0
	v_mov_b64_e32 v[24:25], 0
	v_mov_b64_e32 v[26:27], 0
	v_mov_b64_e32 v[28:29], 0
	v_mov_b64_e32 v[30:31], 0
	v_mov_b64_e32 v[32:33], 0
	v_mov_b64_e32 v[34:35], 0
	v_mov_b64_e32 v[36:37], 0
	v_mov_b64_e32 v[38:39], 0
	v_mov_b64_e32 v[40:41], 0
	v_mov_b64_e32 v[42:43], 0
	v_mov_b64_e32 v[44:45], 0
	v_mov_b64_e32 v[46:47], 0
	v_mov_b64_e32 v[48:49], 0
	v_mov_b64_e32 v[50:51], 0
	v_mov_b64_e32 v[52:53], 0
	v_mov_b64_e32 v[54:55], 0
	v_mov_b64_e32 v[56:57], 0
	v_mov_b64_e32 v[58:59], 0
	v_mov_b64_e32 v[60:61], 0
	v_mov_b64_e32 v[62:63], 0
	v_mov_b64_e32 v[64:65], 0
	v_mov_b64_e32 v[66:67], 0
	v_mov_b64_e32 v[68:69], 0
	v_mov_b64_e32 v[70:71], 0
	v_mov_b64_e32 v[72:73], 0
	v_mov_b64_e32 v[74:75], 0
	v_mov_b64_e32 v[76:77], 0
	v_mov_b64_e32 v[78:79], 0
	v_mov_b64_e32 v[80:81], 0
	v_mov_b64_e32 v[82:83], 0
	v_mov_b64_e32 v[84:85], 0
	v_mov_b64_e32 v[86:87], 0
	v_mov_b64_e32 v[88:89], 0
	v_mov_b64_e32 v[90:91], 0
	v_mov_b64_e32 v[92:93], 0
	v_mov_b64_e32 v[94:95], 0
	v_mov_b64_e32 v[96:97], 0
	v_mov_b64_e32 v[98:99], 0
	v_mov_b64_e32 v[100:101], 0
	v_mov_b64_e32 v[102:103], 0
	v_mov_b64_e32 v[104:105], 0
	v_mov_b64_e32 v[106:107], 0
	v_mov_b64_e32 v[108:109], 0
	v_mov_b64_e32 v[110:111], 0
	v_mov_b64_e32 v[112:113], 0
	v_mov_b64_e32 v[114:115], 0
	v_mov_b64_e32 v[116:117], 0
	v_mov_b64_e32 v[118:119], 0
	v_mov_b64_e32 v[120:121], 0
	v_mov_b64_e32 v[122:123], 0
	v_mov_b64_e32 v[124:125], 0
	v_mov_b64_e32 v[126:127], 0
	.p2align	6

; template <class Epi, class Sched, bool ALIGN_EPI = false, bool SP2 = false>
; __device__ __forceinline__ void gemm_phase(PG8_LAS unsigned char* lds, const Gemm g, const Sched& S, const Epi& E) {
;     ...
;         const char* nA = has_next ? (const char*)g.A + (size_t)nxt.pm * tstep + nxt.ko : cA; const char* nB = has_next ? (const char*)g.Bt + (size_t)nxt.pn * tstep + nxt.ko : cB;
;         for (int t = 0; t < nt; t += 2) {
;             const bool last = (t == nt - 2);
;             const char* a1 = cA + (size_t)(t + 1) * kstep;
;             const char* a2 = last ? nA : cA + (size_t)(t + 2) * kstep; const char* b2 = last ? nB : cB + (size_t)(t + 2) * kstep;
;             const char* a3 = a2 + kstep; const char* b3 = b2 + kstep;
;     ...
; #pragma unroll
;         for (int a = 0; a < 2; ++a)
; #pragma unroll
;             for (int b = 0; b < 2; ++b)
; #pragma unroll
;                 for (int m = 0; m < 4; ++m)
; #pragma unroll
;                     for (int n = 0; n < 2; ++n) acc[a][b][m][n] = (f32x4){0.f, 0.f, 0.f, 0.f};
;         cur = nxt; cA = nA; cB = nB; ++ui;
.LBB0_590:
	v_mov_b32_e32 v127, 0
	s_andn2_b64 vcc, exec, s[34:35]
	v_mov_b64_e32 v[0:1], 0
	v_mov_b64_e32 v[2:3], 0
	v_mov_b64_e32 v[4:5], 0
	v_mov_b64_e32 v[6:7], 0
	v_mov_b64_e32 v[8:9], 0
	v_mov_b64_e32 v[10:11], 0
	v_mov_b64_e32 v[12:13], 0
	v_mov_b64_e32 v[14:15], 0
	v_mov_b64_e32 v[16:17], 0
	v_mov_b64_e32 v[18:19], 0
	v_mov_b64_e32 v[20:21], 0
	v_mov_b64_e32 v[22:23], 0
	v_mov_b64_e32 v[24:25], 0
	v_mov_b64_e32 v[26:27], 0
	v_mov_b64_e32 v[28:29], 0
	v_mov_b64_e32 v[30:31], 0
	v_mov_b64_e32 v[32:33], 0
	v_mov_b64_e32 v[34:35], 0
	v_mov_b64_e32 v[36:37], 0
	v_mov_b64_e32 v[38:39], 0
	v_mov_b64_e32 v[40:41], 0
	v_mov_b64_e32 v[42:43], 0
	v_mov_b64_e32 v[44:45], 0
	v_mov_b64_e32 v[46:47], 0
	v_mov_b64_e32 v[48:49], 0
	v_mov_b64_e32 v[50:51], 0
	v_mov_b64_e32 v[52:53], 0
	v_mov_b64_e32 v[54:55], 0
	v_mov_b64_e32 v[56:57], 0
	v_mov_b64_e32 v[58:59], 0
	v_mov_b64_e32 v[60:61], 0
	v_mov_b64_e32 v[62:63], 0
	v_mov_b64_e32 v[64:65], 0
	v_mov_b64_e32 v[66:67], 0
	v_mov_b64_e32 v[68:69], 0
	v_mov_b64_e32 v[70:71], 0
	v_mov_b64_e32 v[72:73], 0
	v_mov_b64_e32 v[74:75], 0
	v_mov_b64_e32 v[76:77], 0
	v_mov_b64_e32 v[78:79], 0
	v_mov_b64_e32 v[80:81], 0
	v_mov_b64_e32 v[82:83], 0
	v_mov_b64_e32 v[84:85], 0
	v_mov_b64_e32 v[86:87], 0
	v_mov_b64_e32 v[88:89], 0
	v_mov_b64_e32 v[90:91], 0
	v_mov_b64_e32 v[92:93], 0
	v_mov_b64_e32 v[94:95], 0
	v_mov_b64_e32 v[96:97], 0
	v_mov_b64_e32 v[98:99], 0
	v_mov_b64_e32 v[100:101], 0
	v_mov_b64_e32 v[102:103], 0
	v_mov_b64_e32 v[104:105], 0
	v_mov_b64_e32 v[106:107], 0
	v_mov_b64_e32 v[108:109], 0
	v_mov_b64_e32 v[110:111], 0
	v_mov_b64_e32 v[112:113], 0
	v_mov_b64_e32 v[114:115], 0
	v_mov_b64_e32 v[116:117], 0
	v_mov_b64_e32 v[118:119], 0
	v_mov_b64_e32 v[120:121], 0
	v_mov_b64_e32 v[122:123], 0
	v_mov_b64_e32 v[124:125], 0
	v_mov_b64_e32 v[126:127], 0
	s_cbranch_vccnz .LBB0_593
	s_add_u32 s66, s66, 0x80
	s_addc_u32 s67, s67, 0
	s_add_u32 s68, s68, 0x100
	v_mov_b32_e32 v0, 0
	s_addc_u32 s69, s69, 0
	s_mov_b32 s4, 0
	v_mov_b64_e32 v[0:1], 0
	v_mov_b64_e32 v[2:3], 0
	v_mov_b64_e32 v[4:5], 0
	v_mov_b64_e32 v[6:7], 0
	v_mov_b64_e32 v[8:9], 0
	v_mov_b64_e32 v[10:11], 0
	v_mov_b64_e32 v[12:13], 0
	v_mov_b64_e32 v[14:15], 0
	v_mov_b64_e32 v[16:17], 0
	v_mov_b64_e32 v[18:19], 0
	v_mov_b64_e32 v[20:21], 0
	v_mov_b64_e32 v[22:23], 0
	v_mov_b64_e32 v[24:25], 0
	v_mov_b64_e32 v[26:27], 0
	v_mov_b64_e32 v[28:29], 0
	v_mov_b64_e32 v[30:31], 0
	v_mov_b64_e32 v[32:33], 0
	v_mov_b64_e32 v[34:35], 0
	v_mov_b64_e32 v[36:37], 0
	v_mov_b64_e32 v[38:39], 0
	v_mov_b64_e32 v[40:41], 0
	v_mov_b64_e32 v[42:43], 0
	v_mov_b64_e32 v[44:45], 0
	v_mov_b64_e32 v[46:47], 0
	v_mov_b64_e32 v[48:49], 0
	v_mov_b64_e32 v[50:51], 0
	v_mov_b64_e32 v[52:53], 0
	v_mov_b64_e32 v[54:55], 0
	v_mov_b64_e32 v[56:57], 0
	v_mov_b64_e32 v[58:59], 0
	v_mov_b64_e32 v[60:61], 0
	v_mov_b64_e32 v[62:63], 0
	v_mov_b64_e32 v[64:65], 0
	v_mov_b64_e32 v[66:67], 0
	v_mov_b64_e32 v[68:69], 0
	v_mov_b64_e32 v[70:71], 0
	v_mov_b64_e32 v[72:73], 0
	v_mov_b64_e32 v[74:75], 0
	v_mov_b64_e32 v[76:77], 0
	v_mov_b64_e32 v[78:79], 0
	v_mov_b64_e32 v[80:81], 0
	v_mov_b64_e32 v[82:83], 0
	v_mov_b64_e32 v[84:85], 0
	v_mov_b64_e32 v[86:87], 0
	v_mov_b64_e32 v[88:89], 0
	v_mov_b64_e32 v[90:91], 0
	v_mov_b64_e32 v[92:93], 0
	v_mov_b64_e32 v[94:95], 0
	v_mov_b64_e32 v[96:97], 0
	v_mov_b64_e32 v[98:99], 0
	v_mov_b64_e32 v[100:101], 0
	v_mov_b64_e32 v[102:103], 0
	v_mov_b64_e32 v[104:105], 0
	v_mov_b64_e32 v[106:107], 0
	v_mov_b64_e32 v[108:109], 0
	v_mov_b64_e32 v[110:111], 0
	v_mov_b64_e32 v[112:113], 0
	v_mov_b64_e32 v[114:115], 0
	v_mov_b64_e32 v[116:117], 0
	v_mov_b64_e32 v[118:119], 0
	v_mov_b64_e32 v[120:121], 0
	v_mov_b64_e32 v[122:123], 0
	v_mov_b64_e32 v[124:125], 0
	v_mov_b64_e32 v[126:127], 0
	.p2align	6

; template <class Epi, class Sched, bool ALIGN_EPI = false, bool SP2 = false>
; __device__ __forceinline__ void gemm_phase(PG8_LAS unsigned char* lds, const Gemm g, const Sched& S, const Epi& E) {
;     ...
;         const bool has_next = S.next(ui + 1, nxt);
;         const char* nA = has_next ? (const char*)g.A + (size_t)nxt.pm * tstep + nxt.ko : cA; const char* nB = has_next ? (const char*)g.Bt + (size_t)nxt.pn * tstep + nxt.ko : cB;
;         for (int t = 0; t < nt; t += 2) {
;             const bool last = (t == nt - 2);
;             const char* a1 = cA + (size_t)(t + 1) * kstep;
;             const char* a2 = last ? nA : cA + (size_t)(t + 2) * kstep; const char* b2 = last ? nB : cB + (size_t)(t + 2) * kstep;
;             const char* a3 = a2 + kstep; const char* b3 = b2 + kstep;
;     ...
; #pragma unroll
;         for (int a = 0; a < 2; ++a)
; #pragma unroll
;             for (int b = 0; b < 2; ++b)
; #pragma unroll
;                 for (int m = 0; m < 4; ++m)
; #pragma unroll
;                     for (int n = 0; n < 2; ++n) acc[a][b][m][n] = (f32x4){0.f, 0.f, 0.f, 0.f};
;         cur = nxt; cA = nA; cB = nB; ++ui;
.LBB0_717:
	s_ashr_i32 s41, s40, 31
	s_lshl_b64 s[4:5], s[40:41], 19
	s_add_u32 s6, s50, s4
	s_addc_u32 s7, s51, s5
	s_and_b64 s[4:5], s[12:13], exec
	s_cselect_b32 s41, s7, s65
	s_cselect_b32 s76, s6, s64
	s_ashr_i32 s37, s36, 31
	s_lshl_b64 s[4:5], s[36:37], 19
	s_add_u32 s4, s19, s4
	s_addc_u32 s5, s22, s5
	s_and_b64 s[38:39], s[12:13], exec
	s_cselect_b32 s37, s5, s67
	s_cselect_b32 s77, s4, s66
	s_add_u32 vcc_lo, s64, 0x40080
	s_addc_u32 vcc_hi, s65, 0
	s_add_u32 s78, s66, 0x100
	v_mov_b32_e32 v0, 0
	s_addc_u32 s79, s67, 0
	s_mov_b32 s80, -2
	s_cmp_lg_u32 s75, 1
	s_cbranch_scc1 .Lg3_peel
	v_mov_b64_e32 v[0:1], 0
	v_mov_b64_e32 v[2:3], 0
	v_mov_b64_e32 v[4:5], 0
	v_mov_b64_e32 v[6:7], 0
	v_mov_b64_e32 v[8:9], 0
	v_mov_b64_e32 v[10:11], 0
	v_mov_b64_e32 v[12:13], 0
	v_mov_b64_e32 v[14:15], 0
	v_mov_b64_e32 v[16:17], 0
	v_mov_b64_e32 v[18:19], 0
	v_mov_b64_e32 v[20:21], 0
	v_mov_b64_e32 v[22:23], 0
	v_mov_b64_e32 v[24:25], 0
	v_mov_b64_e32 v[26:27], 0
	v_mov_b64_e32 v[28:29], 0
	v_mov_b64_e32 v[30:31], 0
	v_mov_b64_e32 v[32:33], 0
	v_mov_b64_e32 v[34:35], 0
	v_mov_b64_e32 v[36:37], 0
	v_mov_b64_e32 v[38:39], 0
	v_mov_b64_e32 v[40:41], 0
	v_mov_b64_e32 v[42:43], 0
	v_mov_b64_e32 v[44:45], 0
	v_mov_b64_e32 v[46:47], 0
	v_mov_b64_e32 v[48:49], 0
	v_mov_b64_e32 v[50:51], 0
	v_mov_b64_e32 v[52:53], 0
	v_mov_b64_e32 v[54:55], 0
	v_mov_b64_e32 v[56:57], 0
	v_mov_b64_e32 v[58:59], 0
	v_mov_b64_e32 v[60:61], 0
	v_mov_b64_e32 v[62:63], 0
	v_mov_b64_e32 v[64:65], 0
	v_mov_b64_e32 v[66:67], 0
	v_mov_b64_e32 v[68:69], 0
	v_mov_b64_e32 v[70:71], 0
	v_mov_b64_e32 v[72:73], 0
	v_mov_b64_e32 v[74:75], 0
	v_mov_b64_e32 v[76:77], 0
	v_mov_b64_e32 v[78:79], 0
	v_mov_b64_e32 v[80:81], 0
	v_mov_b64_e32 v[82:83], 0
	v_mov_b64_e32 v[84:85], 0
	v_mov_b64_e32 v[86:87], 0
	v_mov_b64_e32 v[88:89], 0
	v_mov_b64_e32 v[90:91], 0
	v_mov_b64_e32 v[92:93], 0
	v_mov_b64_e32 v[94:95], 0
	v_mov_b64_e32 v[96:97], 0
	v_mov_b64_e32 v[98:99], 0
	v_mov_b64_e32 v[100:101], 0
	v_mov_b64_e32 v[102:103], 0
	v_mov_b64_e32 v[104:105], 0
	v_mov_b64_e32 v[106:107], 0
	v_mov_b64_e32 v[108:109], 0
	v_mov_b64_e32 v[110:111], 0
	v_mov_b64_e32 v[112:113], 0
	v_mov_b64_e32 v[114:115], 0
	v_mov_b64_e32 v[116:117], 0
	v_mov_b64_e32 v[118:119], 0
	v_mov_b64_e32 v[120:121], 0
	v_mov_b64_e32 v[122:123], 0
	v_mov_b64_e32 v[124:125], 0
	v_mov_b64_e32 v[126:127], 0
	.p2align	6

; template <class Epi, class Sched, bool ALIGN_EPI = false, bool SP2 = false>
; __device__ __forceinline__ void gemm_phase(PG8_LAS unsigned char* lds, const Gemm g, const Sched& S, const Epi& E) {
;     ...
;         const bool has_next = S.next(ui + 1, nxt);
;         const char* nA = has_next ? (const char*)g.A + (size_t)nxt.pm * tstep + nxt.ko : cA; const char* nB = has_next ? (const char*)g.Bt + (size_t)nxt.pn * tstep + nxt.ko : cB;
;         for (int t = 0; t < nt; t += 2) {
;             const bool last = (t == nt - 2);
;             const char* a1 = cA + (size_t)(t + 1) * kstep;
;             const char* a2 = last ? nA : cA + (size_t)(t + 2) * kstep; const char* b2 = last ? nB : cB + (size_t)(t + 2) * kstep;
;             const char* a3 = a2 + kstep; const char* b3 = b2 + kstep;
;     ...
; #pragma unroll
;         for (int a = 0; a < 2; ++a)
; #pragma unroll
;             for (int b = 0; b < 2; ++b)
; #pragma unroll
;                 for (int m = 0; m < 4; ++m)
; #pragma unroll
;                     for (int n = 0; n < 2; ++n) acc[a][b][m][n] = (f32x4){0.f, 0.f, 0.f, 0.f};
;         cur = nxt; cA = nA; cB = nB; ++ui;
.LBB0_789:
	s_ashr_i32 s35, s34, 31
	s_lshl_b64 s[6:7], s[34:35], 21
	v_readlane_b32 s36, v253, 63
	v_readlane_b32 s37, v254, 0
	s_add_u32 s36, s36, s6
	s_addc_u32 s37, s37, s7
	s_and_b64 s[6:7], s[8:9], exec
	s_cselect_b32 s35, s37, s5
	s_cselect_b32 s72, s36, s4
	s_ashr_i32 s27, s26, 31
	s_lshl_b64 s[6:7], s[26:27], 21
	s_add_u32 s40, s18, s6
	s_addc_u32 s41, s19, s7
	s_and_b64 s[6:7], s[8:9], exec
	s_cselect_b32 s27, s41, s67
	s_cselect_b32 s73, s40, s66
	s_add_u32 s64, s4, 0x100080
	s_addc_u32 s65, s5, 0
	s_add_u32 s66, s66, 0x100
	v_mov_b32_e32 v0, 0
	s_addc_u32 s67, s67, 0
	s_mov_b32 s74, -2
	s_cmp_lg_u32 s69, 1
	s_cbranch_scc1 .Lg4_peel
	v_mov_b64_e32 v[0:1], 0
	v_mov_b64_e32 v[2:3], 0
	v_mov_b64_e32 v[4:5], 0
	v_mov_b64_e32 v[6:7], 0
	v_mov_b64_e32 v[8:9], 0
	v_mov_b64_e32 v[10:11], 0
	v_mov_b64_e32 v[12:13], 0
	v_mov_b64_e32 v[14:15], 0
	v_mov_b64_e32 v[16:17], 0
	v_mov_b64_e32 v[18:19], 0
	v_mov_b64_e32 v[20:21], 0
	v_mov_b64_e32 v[22:23], 0
	v_mov_b64_e32 v[24:25], 0
	v_mov_b64_e32 v[26:27], 0
	v_mov_b64_e32 v[28:29], 0
	v_mov_b64_e32 v[30:31], 0
	v_mov_b64_e32 v[32:33], 0
	v_mov_b64_e32 v[34:35], 0
	v_mov_b64_e32 v[36:37], 0
	v_mov_b64_e32 v[38:39], 0
	v_mov_b64_e32 v[40:41], 0
	v_mov_b64_e32 v[42:43], 0
	v_mov_b64_e32 v[44:45], 0
	v_mov_b64_e32 v[46:47], 0
	v_mov_b64_e32 v[48:49], 0
	v_mov_b64_e32 v[50:51], 0
	v_mov_b64_e32 v[52:53], 0
	v_mov_b64_e32 v[54:55], 0
	v_mov_b64_e32 v[56:57], 0
	v_mov_b64_e32 v[58:59], 0
	v_mov_b64_e32 v[60:61], 0
	v_mov_b64_e32 v[62:63], 0
	v_mov_b64_e32 v[64:65], 0
	v_mov_b64_e32 v[66:67], 0
	v_mov_b64_e32 v[68:69], 0
	v_mov_b64_e32 v[70:71], 0
	v_mov_b64_e32 v[72:73], 0
	v_mov_b64_e32 v[74:75], 0
	v_mov_b64_e32 v[76:77], 0
	v_mov_b64_e32 v[78:79], 0
	v_mov_b64_e32 v[80:81], 0
	v_mov_b64_e32 v[82:83], 0
	v_mov_b64_e32 v[84:85], 0
	v_mov_b64_e32 v[86:87], 0
	v_mov_b64_e32 v[88:89], 0
	v_mov_b64_e32 v[90:91], 0
	v_mov_b64_e32 v[92:93], 0
	v_mov_b64_e32 v[94:95], 0
	v_mov_b64_e32 v[96:97], 0
	v_mov_b64_e32 v[98:99], 0
	v_mov_b64_e32 v[100:101], 0
	v_mov_b64_e32 v[102:103], 0
	v_mov_b64_e32 v[104:105], 0
	v_mov_b64_e32 v[106:107], 0
	v_mov_b64_e32 v[108:109], 0
	v_mov_b64_e32 v[110:111], 0
	v_mov_b64_e32 v[112:113], 0
	v_mov_b64_e32 v[114:115], 0
	v_mov_b64_e32 v[116:117], 0
	v_mov_b64_e32 v[118:119], 0
	v_mov_b64_e32 v[120:121], 0
	v_mov_b64_e32 v[122:123], 0
	v_mov_b64_e32 v[124:125], 0
	v_mov_b64_e32 v[126:127], 0
	.p2align	6

; template <class Epi, class Sched, bool ALIGN_EPI = false, bool SP2 = false>
; __device__ __forceinline__ void gemm_phase(PG8_LAS unsigned char* lds, const Gemm g, const Sched& S, const Epi& E) {
;     ...
;         const char* nA = has_next ? (const char*)g.A + (size_t)nxt.pm * tstep + nxt.ko : cA; const char* nB = has_next ? (const char*)g.Bt + (size_t)nxt.pn * tstep + nxt.ko : cB;
;         for (int t = 0; t < nt; t += 2) {
;             const bool last = (t == nt - 2);
;             const char* a1 = cA + (size_t)(t + 1) * kstep;
;             const char* a2 = last ? nA : cA + (size_t)(t + 2) * kstep; const char* b2 = last ? nB : cB + (size_t)(t + 2) * kstep;
;             const char* a3 = a2 + kstep; const char* b3 = b2 + kstep;
;     ...
; #pragma unroll
;         for (int a = 0; a < 2; ++a)
; #pragma unroll
;             for (int b = 0; b < 2; ++b)
; #pragma unroll
;                 for (int m = 0; m < 4; ++m)
; #pragma unroll
;                     for (int n = 0; n < 2; ++n) acc[a][b][m][n] = (f32x4){0.f, 0.f, 0.f, 0.f};
;         cur = nxt; cA = nA; cB = nB; ++ui;
.LBB0_810:
	v_mov_b32_e32 v127, 0
	s_andn2_b64 vcc, exec, s[26:27]
	v_mov_b64_e32 v[0:1], 0
	v_mov_b64_e32 v[2:3], 0
	v_mov_b64_e32 v[4:5], 0
	v_mov_b64_e32 v[6:7], 0
	v_mov_b64_e32 v[8:9], 0
	v_mov_b64_e32 v[10:11], 0
	v_mov_b64_e32 v[12:13], 0
	v_mov_b64_e32 v[14:15], 0
	v_mov_b64_e32 v[16:17], 0
	v_mov_b64_e32 v[18:19], 0
	v_mov_b64_e32 v[20:21], 0
	v_mov_b64_e32 v[22:23], 0
	v_mov_b64_e32 v[24:25], 0
	v_mov_b64_e32 v[26:27], 0
	v_mov_b64_e32 v[28:29], 0
	v_mov_b64_e32 v[30:31], 0
	v_mov_b64_e32 v[32:33], 0
	v_mov_b64_e32 v[34:35], 0
	v_mov_b64_e32 v[36:37], 0
	v_mov_b64_e32 v[38:39], 0
	v_mov_b64_e32 v[40:41], 0
	v_mov_b64_e32 v[42:43], 0
	v_mov_b64_e32 v[44:45], 0
	v_mov_b64_e32 v[46:47], 0
	v_mov_b64_e32 v[48:49], 0
	v_mov_b64_e32 v[50:51], 0
	v_mov_b64_e32 v[52:53], 0
	v_mov_b64_e32 v[54:55], 0
	v_mov_b64_e32 v[56:57], 0
	v_mov_b64_e32 v[58:59], 0
	v_mov_b64_e32 v[60:61], 0
	v_mov_b64_e32 v[62:63], 0
	v_mov_b64_e32 v[64:65], 0
	v_mov_b64_e32 v[66:67], 0
	v_mov_b64_e32 v[68:69], 0
	v_mov_b64_e32 v[70:71], 0
	v_mov_b64_e32 v[72:73], 0
	v_mov_b64_e32 v[74:75], 0
	v_mov_b64_e32 v[76:77], 0
	v_mov_b64_e32 v[78:79], 0
	v_mov_b64_e32 v[80:81], 0
	v_mov_b64_e32 v[82:83], 0
	v_mov_b64_e32 v[84:85], 0
	v_mov_b64_e32 v[86:87], 0
	v_mov_b64_e32 v[88:89], 0
	v_mov_b64_e32 v[90:91], 0
	v_mov_b64_e32 v[92:93], 0
	v_mov_b64_e32 v[94:95], 0
	v_mov_b64_e32 v[96:97], 0
	v_mov_b64_e32 v[98:99], 0
	v_mov_b64_e32 v[100:101], 0
	v_mov_b64_e32 v[102:103], 0
	v_mov_b64_e32 v[104:105], 0
	v_mov_b64_e32 v[106:107], 0
	v_mov_b64_e32 v[108:109], 0
	v_mov_b64_e32 v[110:111], 0
	v_mov_b64_e32 v[112:113], 0
	v_mov_b64_e32 v[114:115], 0
	v_mov_b64_e32 v[116:117], 0
	v_mov_b64_e32 v[118:119], 0
	v_mov_b64_e32 v[120:121], 0
	v_mov_b64_e32 v[122:123], 0
	v_mov_b64_e32 v[124:125], 0
	v_mov_b64_e32 v[126:127], 0
	s_cbranch_vccnz .LBB0_813
	s_add_u32 s64, s64, 0x80
	s_addc_u32 s65, s65, 0
	s_add_u32 s66, s66, 0x100
	v_mov_b32_e32 v0, 0
	s_addc_u32 s67, s67, 0
	s_mov_b32 s4, 0
	v_mov_b64_e32 v[0:1], 0
	v_mov_b64_e32 v[2:3], 0
	v_mov_b64_e32 v[4:5], 0
	v_mov_b64_e32 v[6:7], 0
	v_mov_b64_e32 v[8:9], 0
	v_mov_b64_e32 v[10:11], 0
	v_mov_b64_e32 v[12:13], 0
	v_mov_b64_e32 v[14:15], 0
	v_mov_b64_e32 v[16:17], 0
	v_mov_b64_e32 v[18:19], 0
	v_mov_b64_e32 v[20:21], 0
	v_mov_b64_e32 v[22:23], 0
	v_mov_b64_e32 v[24:25], 0
	v_mov_b64_e32 v[26:27], 0
	v_mov_b64_e32 v[28:29], 0
	v_mov_b64_e32 v[30:31], 0
	v_mov_b64_e32 v[32:33], 0
	v_mov_b64_e32 v[34:35], 0
	v_mov_b64_e32 v[36:37], 0
	v_mov_b64_e32 v[38:39], 0
	v_mov_b64_e32 v[40:41], 0
	v_mov_b64_e32 v[42:43], 0
	v_mov_b64_e32 v[44:45], 0
	v_mov_b64_e32 v[46:47], 0
	v_mov_b64_e32 v[48:49], 0
	v_mov_b64_e32 v[50:51], 0
	v_mov_b64_e32 v[52:53], 0
	v_mov_b64_e32 v[54:55], 0
	v_mov_b64_e32 v[56:57], 0
	v_mov_b64_e32 v[58:59], 0
	v_mov_b64_e32 v[60:61], 0
	v_mov_b64_e32 v[62:63], 0
	v_mov_b64_e32 v[64:65], 0
	v_mov_b64_e32 v[66:67], 0
	v_mov_b64_e32 v[68:69], 0
	v_mov_b64_e32 v[70:71], 0
	v_mov_b64_e32 v[72:73], 0
	v_mov_b64_e32 v[74:75], 0
	v_mov_b64_e32 v[76:77], 0
	v_mov_b64_e32 v[78:79], 0
	v_mov_b64_e32 v[80:81], 0
	v_mov_b64_e32 v[82:83], 0
	v_mov_b64_e32 v[84:85], 0
	v_mov_b64_e32 v[86:87], 0
	v_mov_b64_e32 v[88:89], 0
	v_mov_b64_e32 v[90:91], 0
	v_mov_b64_e32 v[92:93], 0
	v_mov_b64_e32 v[94:95], 0
	v_mov_b64_e32 v[96:97], 0
	v_mov_b64_e32 v[98:99], 0
	v_mov_b64_e32 v[100:101], 0
	v_mov_b64_e32 v[102:103], 0
	v_mov_b64_e32 v[104:105], 0
	v_mov_b64_e32 v[106:107], 0
	v_mov_b64_e32 v[108:109], 0
	v_mov_b64_e32 v[110:111], 0
	v_mov_b64_e32 v[112:113], 0
	v_mov_b64_e32 v[114:115], 0
	v_mov_b64_e32 v[116:117], 0
	v_mov_b64_e32 v[118:119], 0
	v_mov_b64_e32 v[120:121], 0
	v_mov_b64_e32 v[122:123], 0
	v_mov_b64_e32 v[124:125], 0
	v_mov_b64_e32 v[126:127], 0
	.p2align	6
